# rw_scan: the two packed-f32 y ops separated (one wait state between a packed result and its dependent read); otherwise as previous
# speedup vs baseline: 1.0685x; 1.0011x over previous
; __device__ __forceinline__ void phase_rw_scan(KP P, const Ctx& c) {
;     ...
;             RW_LLOAD(A, 0);
; #pragma unroll 1
;             for (int tk = 0; tk < 64; tk += 2) {
;                 RW_LLOAD(B, tk + 1);
;                 RW_STEP(A, tk);
;                 RW_LLOAD(A, (tk + 2) & 63);
;                 RW_STEP(B, tk + 1);
;             }
.Lrw_loop:
	s_waitcnt lgkmcnt(9)
	v_pk_mul_f32 v[230:231], v[170:171], v[38:39] op_sel_hi:[1,0]
	v_pk_mul_f32 v[232:233], v[170:171], v[46:47] op_sel_hi:[1,0]
	v_pk_fma_f32 v[230:231], v[172:173], v[38:39], v[230:231] op_sel:[0,1,0]
	v_pk_fma_f32 v[232:233], v[172:173], v[46:47], v[232:233] op_sel:[0,1,0]
	v_pk_fma_f32 v[230:231], v[174:175], v[40:41], v[230:231] op_sel_hi:[1,0,1]
	v_pk_fma_f32 v[232:233], v[174:175], v[48:49], v[232:233] op_sel_hi:[1,0,1]
	v_pk_fma_f32 v[230:231], v[176:177], v[40:41], v[230:231] op_sel:[0,1,0]
	v_pk_fma_f32 v[232:233], v[176:177], v[48:49], v[232:233] op_sel:[0,1,0]
	v_pk_fma_f32 v[230:231], v[178:179], v[42:43], v[230:231] op_sel_hi:[1,0,1]
	v_pk_fma_f32 v[232:233], v[178:179], v[50:51], v[232:233] op_sel_hi:[1,0,1]
	v_pk_fma_f32 v[230:231], v[180:181], v[42:43], v[230:231] op_sel:[0,1,0]
	v_pk_fma_f32 v[232:233], v[180:181], v[50:51], v[232:233] op_sel:[0,1,0]
	v_pk_fma_f32 v[230:231], v[182:183], v[44:45], v[230:231] op_sel_hi:[1,0,1]
	v_pk_fma_f32 v[232:233], v[182:183], v[52:53], v[232:233] op_sel_hi:[1,0,1]
	v_pk_fma_f32 v[230:231], v[184:185], v[44:45], v[230:231] op_sel:[0,1,0]
	v_pk_fma_f32 v[232:233], v[184:185], v[52:53], v[232:233] op_sel:[0,1,0]
	ds_read_b128 v[186:189], v240 offset:33024
	ds_read_b128 v[190:193], v240 offset:33040
	ds_read_b128 v[194:197], v240 offset:256
	ds_read_b128 v[198:201], v240 offset:272
	s_waitcnt lgkmcnt(8)
	v_pk_mul_f32 v[82:83], v[170:171], v[54:55] op_sel_hi:[1,0]
	v_pk_mul_f32 v[84:85], v[172:173], v[54:55] op_sel:[0,1]
	v_pk_mul_f32 v[86:87], v[174:175], v[56:57] op_sel_hi:[1,0]
	v_pk_mul_f32 v[88:89], v[176:177], v[56:57] op_sel:[0,1]
	v_add_f32_dpp v230, v230, v230 quad_perm:[1,0,3,2] row_mask:0xf bank_mask:0xf
	v_pk_mul_f32 v[90:91], v[178:179], v[58:59] op_sel_hi:[1,0]
	v_add_f32_dpp v231, v231, v231 quad_perm:[1,0,3,2] row_mask:0xf bank_mask:0xf
	v_pk_mul_f32 v[92:93], v[180:181], v[58:59] op_sel:[0,1]
	v_add_f32_dpp v232, v232, v232 quad_perm:[1,0,3,2] row_mask:0xf bank_mask:0xf
	v_pk_mul_f32 v[94:95], v[182:183], v[60:61] op_sel_hi:[1,0]
	v_add_f32_dpp v233, v233, v233 quad_perm:[1,0,3,2] row_mask:0xf bank_mask:0xf
	v_pk_mul_f32 v[96:97], v[184:185], v[60:61] op_sel:[0,1]
	v_add_f32_dpp v230, v230, v230 quad_perm:[2,3,0,1] row_mask:0xf bank_mask:0xf
	v_pk_fma_f32 v[82:83], v[78:79], v[62:63], v[82:83] op_sel_hi:[1,0,1]
	v_add_f32_dpp v231, v231, v231 quad_perm:[2,3,0,1] row_mask:0xf bank_mask:0xf
	v_pk_fma_f32 v[84:85], v[78:79], v[62:63], v[84:85] op_sel:[0,1,0]
	v_add_f32_dpp v232, v232, v232 quad_perm:[2,3,0,1] row_mask:0xf bank_mask:0xf
	v_pk_fma_f32 v[86:87], v[78:79], v[64:65], v[86:87] op_sel_hi:[1,0,1]
	v_add_f32_dpp v233, v233, v233 quad_perm:[2,3,0,1] row_mask:0xf bank_mask:0xf
	v_pk_fma_f32 v[88:89], v[78:79], v[64:65], v[88:89] op_sel:[0,1,0]
	v_add_f32_dpp v230, v230, v230 row_half_mirror row_mask:0xf bank_mask:0xf
	v_pk_fma_f32 v[90:91], v[78:79], v[66:67], v[90:91] op_sel_hi:[1,0,1]
	v_add_f32_dpp v231, v231, v231 row_half_mirror row_mask:0xf bank_mask:0xf
	v_pk_fma_f32 v[92:93], v[78:79], v[66:67], v[92:93] op_sel:[0,1,0]
	v_add_f32_dpp v232, v232, v232 row_half_mirror row_mask:0xf bank_mask:0xf
	v_pk_fma_f32 v[94:95], v[78:79], v[68:69], v[94:95] op_sel_hi:[1,0,1]
	v_add_f32_dpp v233, v233, v233 row_half_mirror row_mask:0xf bank_mask:0xf
	v_pk_fma_f32 v[96:97], v[78:79], v[68:69], v[96:97] op_sel:[0,1,0]
	ds_read_b128 v[202:205], v240 offset:16640
	ds_read_b128 v[206:209], v240 offset:16656
	ds_read_b128 v[210:213], v241 offset:256
	ds_read_b128 v[214:217], v241 offset:272
	ds_read_b64 v[226:227], v242 offset:256
	s_waitcnt lgkmcnt(10)
	v_pk_fma_f32 v[234:235], v[230:231], v[80:81], v[232:233] op_sel_hi:[1,0,1] neg_lo:[1,0,0] neg_hi:[1,0,0]
	v_pk_fma_f32 v[170:171], v[230:231], v[70:71], v[82:83] op_sel_hi:[1,0,1] neg_lo:[1,0,0] neg_hi:[1,0,0]
	v_pk_fma_f32 v[172:173], v[230:231], v[70:71], v[84:85] op_sel:[0,1,0] neg_lo:[1,0,0] neg_hi:[1,0,0]
	v_pk_fma_f32 v[174:175], v[230:231], v[72:73], v[86:87] op_sel_hi:[1,0,1] neg_lo:[1,0,0] neg_hi:[1,0,0]
	v_pk_fma_f32 v[176:177], v[230:231], v[72:73], v[88:89] op_sel:[0,1,0] neg_lo:[1,0,0] neg_hi:[1,0,0]
	v_pk_fma_f32 v[178:179], v[230:231], v[74:75], v[90:91] op_sel_hi:[1,0,1] neg_lo:[1,0,0] neg_hi:[1,0,0]
	v_pk_fma_f32 v[180:181], v[230:231], v[74:75], v[92:93] op_sel:[0,1,0] neg_lo:[1,0,0] neg_hi:[1,0,0]
	v_pk_fma_f32 v[182:183], v[230:231], v[76:77], v[94:95] op_sel_hi:[1,0,1] neg_lo:[1,0,0] neg_hi:[1,0,0]
	v_pk_fma_f32 v[184:185], v[230:231], v[76:77], v[96:97] op_sel:[0,1,0] neg_lo:[1,0,0] neg_hi:[1,0,0]
	v_pk_fma_f32 v[234:235], v[78:79], v[80:81], v[234:235] op_sel:[0,1,0]
	ds_read_b128 v[218:221], v240 offset:49408
	ds_read_b128 v[222:225], v240 offset:49424
	ds_read_b64 v[228:229], v243 offset:8
	s_mov_b64 exec, s[60:61]
	ds_write_b64 v242, v[234:235] offset:16384
	s_mov_b64 exec, -1
	s_waitcnt lgkmcnt(9)
	v_pk_mul_f32 v[230:231], v[170:171], v[186:187] op_sel_hi:[1,0]
	v_pk_mul_f32 v[232:233], v[170:171], v[194:195] op_sel_hi:[1,0]
	v_pk_fma_f32 v[230:231], v[172:173], v[186:187], v[230:231] op_sel:[0,1,0]
	v_pk_fma_f32 v[232:233], v[172:173], v[194:195], v[232:233] op_sel:[0,1,0]
	v_pk_fma_f32 v[230:231], v[174:175], v[188:189], v[230:231] op_sel_hi:[1,0,1]
	v_pk_fma_f32 v[232:233], v[174:175], v[196:197], v[232:233] op_sel_hi:[1,0,1]
	v_pk_fma_f32 v[230:231], v[176:177], v[188:189], v[230:231] op_sel:[0,1,0]
	v_pk_fma_f32 v[232:233], v[176:177], v[196:197], v[232:233] op_sel:[0,1,0]
	v_pk_fma_f32 v[230:231], v[178:179], v[190:191], v[230:231] op_sel_hi:[1,0,1]
	v_pk_fma_f32 v[232:233], v[178:179], v[198:199], v[232:233] op_sel_hi:[1,0,1]
	v_pk_fma_f32 v[230:231], v[180:181], v[190:191], v[230:231] op_sel:[0,1,0]
	v_pk_fma_f32 v[232:233], v[180:181], v[198:199], v[232:233] op_sel:[0,1,0]
	v_pk_fma_f32 v[230:231], v[182:183], v[192:193], v[230:231] op_sel_hi:[1,0,1]
	v_pk_fma_f32 v[232:233], v[182:183], v[200:201], v[232:233] op_sel_hi:[1,0,1]
	v_pk_fma_f32 v[230:231], v[184:185], v[192:193], v[230:231] op_sel:[0,1,0]
	v_pk_fma_f32 v[232:233], v[184:185], v[200:201], v[232:233] op_sel:[0,1,0]
	ds_read_b128 v[38:41], v240 offset:33280
	ds_read_b128 v[42:45], v240 offset:33296
	ds_read_b128 v[46:49], v240 offset:512
	ds_read_b128 v[50:53], v240 offset:528
	s_waitcnt lgkmcnt(8)
; __device__ __forceinline__ void phase_rw_scan(KP P, const Ctx& c) {
;     ...
;             RW_LLOAD(A, 0);
; #pragma unroll 1
;             for (int tk = 0; tk < 64; tk += 2) {
;                 RW_LLOAD(B, tk + 1);
;                 RW_STEP(A, tk);
;                 RW_LLOAD(A, (tk + 2) & 63);
;                 RW_STEP(B, tk + 1);
;             }
	v_pk_mul_f32 v[82:83], v[170:171], v[202:203] op_sel_hi:[1,0]
	v_pk_mul_f32 v[84:85], v[172:173], v[202:203] op_sel:[0,1]
	v_pk_mul_f32 v[86:87], v[174:175], v[204:205] op_sel_hi:[1,0]
	v_pk_mul_f32 v[88:89], v[176:177], v[204:205] op_sel:[0,1]
	v_add_f32_dpp v230, v230, v230 quad_perm:[1,0,3,2] row_mask:0xf bank_mask:0xf
	v_pk_mul_f32 v[90:91], v[178:179], v[206:207] op_sel_hi:[1,0]
	v_add_f32_dpp v231, v231, v231 quad_perm:[1,0,3,2] row_mask:0xf bank_mask:0xf
	v_pk_mul_f32 v[92:93], v[180:181], v[206:207] op_sel:[0,1]
	v_add_f32_dpp v232, v232, v232 quad_perm:[1,0,3,2] row_mask:0xf bank_mask:0xf
	v_pk_mul_f32 v[94:95], v[182:183], v[208:209] op_sel_hi:[1,0]
	v_add_f32_dpp v233, v233, v233 quad_perm:[1,0,3,2] row_mask:0xf bank_mask:0xf
	v_pk_mul_f32 v[96:97], v[184:185], v[208:209] op_sel:[0,1]
	v_add_f32_dpp v230, v230, v230 quad_perm:[2,3,0,1] row_mask:0xf bank_mask:0xf
	v_pk_fma_f32 v[82:83], v[226:227], v[210:211], v[82:83] op_sel_hi:[1,0,1]
	v_add_f32_dpp v231, v231, v231 quad_perm:[2,3,0,1] row_mask:0xf bank_mask:0xf
	v_pk_fma_f32 v[84:85], v[226:227], v[210:211], v[84:85] op_sel:[0,1,0]
	v_add_f32_dpp v232, v232, v232 quad_perm:[2,3,0,1] row_mask:0xf bank_mask:0xf
	v_pk_fma_f32 v[86:87], v[226:227], v[212:213], v[86:87] op_sel_hi:[1,0,1]
	v_add_f32_dpp v233, v233, v233 quad_perm:[2,3,0,1] row_mask:0xf bank_mask:0xf
	v_pk_fma_f32 v[88:89], v[226:227], v[212:213], v[88:89] op_sel:[0,1,0]
	v_add_f32_dpp v230, v230, v230 row_half_mirror row_mask:0xf bank_mask:0xf
	v_pk_fma_f32 v[90:91], v[226:227], v[214:215], v[90:91] op_sel_hi:[1,0,1]
	v_add_f32_dpp v231, v231, v231 row_half_mirror row_mask:0xf bank_mask:0xf
	v_pk_fma_f32 v[92:93], v[226:227], v[214:215], v[92:93] op_sel:[0,1,0]
	v_add_f32_dpp v232, v232, v232 row_half_mirror row_mask:0xf bank_mask:0xf
	v_pk_fma_f32 v[94:95], v[226:227], v[216:217], v[94:95] op_sel_hi:[1,0,1]
	v_add_f32_dpp v233, v233, v233 row_half_mirror row_mask:0xf bank_mask:0xf
	v_pk_fma_f32 v[96:97], v[226:227], v[216:217], v[96:97] op_sel:[0,1,0]
	ds_read_b128 v[54:57], v240 offset:16896
	ds_read_b128 v[58:61], v240 offset:16912
	ds_read_b128 v[62:65], v241 offset:512
	ds_read_b128 v[66:69], v241 offset:528
	ds_read_b64 v[78:79], v242 offset:512
	s_waitcnt lgkmcnt(10)
	v_pk_fma_f32 v[234:235], v[230:231], v[228:229], v[232:233] op_sel_hi:[1,0,1] neg_lo:[1,0,0] neg_hi:[1,0,0]
	v_pk_fma_f32 v[170:171], v[230:231], v[218:219], v[82:83] op_sel_hi:[1,0,1] neg_lo:[1,0,0] neg_hi:[1,0,0]
	v_pk_fma_f32 v[172:173], v[230:231], v[218:219], v[84:85] op_sel:[0,1,0] neg_lo:[1,0,0] neg_hi:[1,0,0]
	v_pk_fma_f32 v[174:175], v[230:231], v[220:221], v[86:87] op_sel_hi:[1,0,1] neg_lo:[1,0,0] neg_hi:[1,0,0]
	v_pk_fma_f32 v[176:177], v[230:231], v[220:221], v[88:89] op_sel:[0,1,0] neg_lo:[1,0,0] neg_hi:[1,0,0]
	v_pk_fma_f32 v[178:179], v[230:231], v[222:223], v[90:91] op_sel_hi:[1,0,1] neg_lo:[1,0,0] neg_hi:[1,0,0]
	v_pk_fma_f32 v[180:181], v[230:231], v[222:223], v[92:93] op_sel:[0,1,0] neg_lo:[1,0,0] neg_hi:[1,0,0]
	v_pk_fma_f32 v[182:183], v[230:231], v[224:225], v[94:95] op_sel_hi:[1,0,1] neg_lo:[1,0,0] neg_hi:[1,0,0]
	v_pk_fma_f32 v[184:185], v[230:231], v[224:225], v[96:97] op_sel:[0,1,0] neg_lo:[1,0,0] neg_hi:[1,0,0]
	v_pk_fma_f32 v[234:235], v[226:227], v[228:229], v[234:235] op_sel:[0,1,0]
	ds_read_b128 v[70:73], v240 offset:49664
	ds_read_b128 v[74:77], v240 offset:49680
	ds_read_b64 v[80:81], v243 offset:16
	s_mov_b64 exec, s[60:61]
	ds_write_b64 v242, v[234:235] offset:16640
	s_mov_b64 exec, -1
	s_waitcnt lgkmcnt(9)
	v_pk_mul_f32 v[230:231], v[170:171], v[38:39] op_sel_hi:[1,0]
	v_pk_mul_f32 v[232:233], v[170:171], v[46:47] op_sel_hi:[1,0]
	v_pk_fma_f32 v[230:231], v[172:173], v[38:39], v[230:231] op_sel:[0,1,0]
	v_pk_fma_f32 v[232:233], v[172:173], v[46:47], v[232:233] op_sel:[0,1,0]
	v_pk_fma_f32 v[230:231], v[174:175], v[40:41], v[230:231] op_sel_hi:[1,0,1]
	v_pk_fma_f32 v[232:233], v[174:175], v[48:49], v[232:233] op_sel_hi:[1,0,1]
	v_pk_fma_f32 v[230:231], v[176:177], v[40:41], v[230:231] op_sel:[0,1,0]
	v_pk_fma_f32 v[232:233], v[176:177], v[48:49], v[232:233] op_sel:[0,1,0]
	v_pk_fma_f32 v[230:231], v[178:179], v[42:43], v[230:231] op_sel_hi:[1,0,1]
	v_pk_fma_f32 v[232:233], v[178:179], v[50:51], v[232:233] op_sel_hi:[1,0,1]
	v_pk_fma_f32 v[230:231], v[180:181], v[42:43], v[230:231] op_sel:[0,1,0]
	v_pk_fma_f32 v[232:233], v[180:181], v[50:51], v[232:233] op_sel:[0,1,0]
	v_pk_fma_f32 v[230:231], v[182:183], v[44:45], v[230:231] op_sel_hi:[1,0,1]
	v_pk_fma_f32 v[232:233], v[182:183], v[52:53], v[232:233] op_sel_hi:[1,0,1]
	v_pk_fma_f32 v[230:231], v[184:185], v[44:45], v[230:231] op_sel:[0,1,0]
	v_pk_fma_f32 v[232:233], v[184:185], v[52:53], v[232:233] op_sel:[0,1,0]
	ds_read_b128 v[186:189], v240 offset:33536
	ds_read_b128 v[190:193], v240 offset:33552
	ds_read_b128 v[194:197], v240 offset:768
	ds_read_b128 v[198:201], v240 offset:784
	s_waitcnt lgkmcnt(8)
; __device__ __forceinline__ void phase_rw_scan(KP P, const Ctx& c) {
;     ...
;             RW_LLOAD(A, 0);
; #pragma unroll 1
;             for (int tk = 0; tk < 64; tk += 2) {
;                 RW_LLOAD(B, tk + 1);
;                 RW_STEP(A, tk);
;                 RW_LLOAD(A, (tk + 2) & 63);
;                 RW_STEP(B, tk + 1);
;             }
	v_pk_mul_f32 v[82:83], v[170:171], v[54:55] op_sel_hi:[1,0]
	v_pk_mul_f32 v[84:85], v[172:173], v[54:55] op_sel:[0,1]
	v_pk_mul_f32 v[86:87], v[174:175], v[56:57] op_sel_hi:[1,0]
	v_pk_mul_f32 v[88:89], v[176:177], v[56:57] op_sel:[0,1]
	v_add_f32_dpp v230, v230, v230 quad_perm:[1,0,3,2] row_mask:0xf bank_mask:0xf
	v_pk_mul_f32 v[90:91], v[178:179], v[58:59] op_sel_hi:[1,0]
	v_add_f32_dpp v231, v231, v231 quad_perm:[1,0,3,2] row_mask:0xf bank_mask:0xf
	v_pk_mul_f32 v[92:93], v[180:181], v[58:59] op_sel:[0,1]
	v_add_f32_dpp v232, v232, v232 quad_perm:[1,0,3,2] row_mask:0xf bank_mask:0xf
	v_pk_mul_f32 v[94:95], v[182:183], v[60:61] op_sel_hi:[1,0]
	v_add_f32_dpp v233, v233, v233 quad_perm:[1,0,3,2] row_mask:0xf bank_mask:0xf
	v_pk_mul_f32 v[96:97], v[184:185], v[60:61] op_sel:[0,1]
	v_add_f32_dpp v230, v230, v230 quad_perm:[2,3,0,1] row_mask:0xf bank_mask:0xf
	v_pk_fma_f32 v[82:83], v[78:79], v[62:63], v[82:83] op_sel_hi:[1,0,1]
	v_add_f32_dpp v231, v231, v231 quad_perm:[2,3,0,1] row_mask:0xf bank_mask:0xf
	v_pk_fma_f32 v[84:85], v[78:79], v[62:63], v[84:85] op_sel:[0,1,0]
	v_add_f32_dpp v232, v232, v232 quad_perm:[2,3,0,1] row_mask:0xf bank_mask:0xf
	v_pk_fma_f32 v[86:87], v[78:79], v[64:65], v[86:87] op_sel_hi:[1,0,1]
	v_add_f32_dpp v233, v233, v233 quad_perm:[2,3,0,1] row_mask:0xf bank_mask:0xf
	v_pk_fma_f32 v[88:89], v[78:79], v[64:65], v[88:89] op_sel:[0,1,0]
	v_add_f32_dpp v230, v230, v230 row_half_mirror row_mask:0xf bank_mask:0xf
	v_pk_fma_f32 v[90:91], v[78:79], v[66:67], v[90:91] op_sel_hi:[1,0,1]
	v_add_f32_dpp v231, v231, v231 row_half_mirror row_mask:0xf bank_mask:0xf
	v_pk_fma_f32 v[92:93], v[78:79], v[66:67], v[92:93] op_sel:[0,1,0]
	v_add_f32_dpp v232, v232, v232 row_half_mirror row_mask:0xf bank_mask:0xf
	v_pk_fma_f32 v[94:95], v[78:79], v[68:69], v[94:95] op_sel_hi:[1,0,1]
	v_add_f32_dpp v233, v233, v233 row_half_mirror row_mask:0xf bank_mask:0xf
	v_pk_fma_f32 v[96:97], v[78:79], v[68:69], v[96:97] op_sel:[0,1,0]
	ds_read_b128 v[202:205], v240 offset:17152
	ds_read_b128 v[206:209], v240 offset:17168
	ds_read_b128 v[210:213], v241 offset:768
	ds_read_b128 v[214:217], v241 offset:784
	ds_read_b64 v[226:227], v242 offset:768
	s_waitcnt lgkmcnt(10)
	v_pk_fma_f32 v[234:235], v[230:231], v[80:81], v[232:233] op_sel_hi:[1,0,1] neg_lo:[1,0,0] neg_hi:[1,0,0]
	v_pk_fma_f32 v[170:171], v[230:231], v[70:71], v[82:83] op_sel_hi:[1,0,1] neg_lo:[1,0,0] neg_hi:[1,0,0]
	v_pk_fma_f32 v[172:173], v[230:231], v[70:71], v[84:85] op_sel:[0,1,0] neg_lo:[1,0,0] neg_hi:[1,0,0]
	v_pk_fma_f32 v[174:175], v[230:231], v[72:73], v[86:87] op_sel_hi:[1,0,1] neg_lo:[1,0,0] neg_hi:[1,0,0]
	v_pk_fma_f32 v[176:177], v[230:231], v[72:73], v[88:89] op_sel:[0,1,0] neg_lo:[1,0,0] neg_hi:[1,0,0]
	v_pk_fma_f32 v[178:179], v[230:231], v[74:75], v[90:91] op_sel_hi:[1,0,1] neg_lo:[1,0,0] neg_hi:[1,0,0]
	v_pk_fma_f32 v[180:181], v[230:231], v[74:75], v[92:93] op_sel:[0,1,0] neg_lo:[1,0,0] neg_hi:[1,0,0]
	v_pk_fma_f32 v[182:183], v[230:231], v[76:77], v[94:95] op_sel_hi:[1,0,1] neg_lo:[1,0,0] neg_hi:[1,0,0]
	v_pk_fma_f32 v[184:185], v[230:231], v[76:77], v[96:97] op_sel:[0,1,0] neg_lo:[1,0,0] neg_hi:[1,0,0]
	v_pk_fma_f32 v[234:235], v[78:79], v[80:81], v[234:235] op_sel:[0,1,0]
	ds_read_b128 v[218:221], v240 offset:49920
	ds_read_b128 v[222:225], v240 offset:49936
	ds_read_b64 v[228:229], v243 offset:24
	s_mov_b64 exec, s[60:61]
	ds_write_b64 v242, v[234:235] offset:16896
	s_mov_b64 exec, -1
	s_waitcnt lgkmcnt(9)
	v_pk_mul_f32 v[230:231], v[170:171], v[186:187] op_sel_hi:[1,0]
	v_pk_mul_f32 v[232:233], v[170:171], v[194:195] op_sel_hi:[1,0]
	v_pk_fma_f32 v[230:231], v[172:173], v[186:187], v[230:231] op_sel:[0,1,0]
	v_pk_fma_f32 v[232:233], v[172:173], v[194:195], v[232:233] op_sel:[0,1,0]
	v_pk_fma_f32 v[230:231], v[174:175], v[188:189], v[230:231] op_sel_hi:[1,0,1]
	v_pk_fma_f32 v[232:233], v[174:175], v[196:197], v[232:233] op_sel_hi:[1,0,1]
	v_pk_fma_f32 v[230:231], v[176:177], v[188:189], v[230:231] op_sel:[0,1,0]
	v_pk_fma_f32 v[232:233], v[176:177], v[196:197], v[232:233] op_sel:[0,1,0]
	v_pk_fma_f32 v[230:231], v[178:179], v[190:191], v[230:231] op_sel_hi:[1,0,1]
	v_pk_fma_f32 v[232:233], v[178:179], v[198:199], v[232:233] op_sel_hi:[1,0,1]
	v_pk_fma_f32 v[230:231], v[180:181], v[190:191], v[230:231] op_sel:[0,1,0]
	v_pk_fma_f32 v[232:233], v[180:181], v[198:199], v[232:233] op_sel:[0,1,0]
	v_pk_fma_f32 v[230:231], v[182:183], v[192:193], v[230:231] op_sel_hi:[1,0,1]
	v_pk_fma_f32 v[232:233], v[182:183], v[200:201], v[232:233] op_sel_hi:[1,0,1]
	v_pk_fma_f32 v[230:231], v[184:185], v[192:193], v[230:231] op_sel:[0,1,0]
	v_pk_fma_f32 v[232:233], v[184:185], v[200:201], v[232:233] op_sel:[0,1,0]
	ds_read_b128 v[38:41], v240 offset:33792
	ds_read_b128 v[42:45], v240 offset:33808
	ds_read_b128 v[46:49], v240 offset:1024
	ds_read_b128 v[50:53], v240 offset:1040
	s_waitcnt lgkmcnt(8)
; __device__ __forceinline__ void phase_rw_scan(KP P, const Ctx& c) {
;     ...
;             RW_LLOAD(A, 0);
; #pragma unroll 1
;             for (int tk = 0; tk < 64; tk += 2) {
;                 RW_LLOAD(B, tk + 1);
;                 RW_STEP(A, tk);
;                 RW_LLOAD(A, (tk + 2) & 63);
;                 RW_STEP(B, tk + 1);
;             }
	v_pk_mul_f32 v[82:83], v[170:171], v[202:203] op_sel_hi:[1,0]
	v_pk_mul_f32 v[84:85], v[172:173], v[202:203] op_sel:[0,1]
	v_pk_mul_f32 v[86:87], v[174:175], v[204:205] op_sel_hi:[1,0]
	v_pk_mul_f32 v[88:89], v[176:177], v[204:205] op_sel:[0,1]
	v_add_f32_dpp v230, v230, v230 quad_perm:[1,0,3,2] row_mask:0xf bank_mask:0xf
	v_pk_mul_f32 v[90:91], v[178:179], v[206:207] op_sel_hi:[1,0]
	v_add_f32_dpp v231, v231, v231 quad_perm:[1,0,3,2] row_mask:0xf bank_mask:0xf
	v_pk_mul_f32 v[92:93], v[180:181], v[206:207] op_sel:[0,1]
	v_add_f32_dpp v232, v232, v232 quad_perm:[1,0,3,2] row_mask:0xf bank_mask:0xf
	v_pk_mul_f32 v[94:95], v[182:183], v[208:209] op_sel_hi:[1,0]
	v_add_f32_dpp v233, v233, v233 quad_perm:[1,0,3,2] row_mask:0xf bank_mask:0xf
	v_pk_mul_f32 v[96:97], v[184:185], v[208:209] op_sel:[0,1]
	v_add_f32_dpp v230, v230, v230 quad_perm:[2,3,0,1] row_mask:0xf bank_mask:0xf
	v_pk_fma_f32 v[82:83], v[226:227], v[210:211], v[82:83] op_sel_hi:[1,0,1]
	v_add_f32_dpp v231, v231, v231 quad_perm:[2,3,0,1] row_mask:0xf bank_mask:0xf
	v_pk_fma_f32 v[84:85], v[226:227], v[210:211], v[84:85] op_sel:[0,1,0]
	v_add_f32_dpp v232, v232, v232 quad_perm:[2,3,0,1] row_mask:0xf bank_mask:0xf
	v_pk_fma_f32 v[86:87], v[226:227], v[212:213], v[86:87] op_sel_hi:[1,0,1]
	v_add_f32_dpp v233, v233, v233 quad_perm:[2,3,0,1] row_mask:0xf bank_mask:0xf
	v_pk_fma_f32 v[88:89], v[226:227], v[212:213], v[88:89] op_sel:[0,1,0]
	v_add_f32_dpp v230, v230, v230 row_half_mirror row_mask:0xf bank_mask:0xf
	v_pk_fma_f32 v[90:91], v[226:227], v[214:215], v[90:91] op_sel_hi:[1,0,1]
	v_add_f32_dpp v231, v231, v231 row_half_mirror row_mask:0xf bank_mask:0xf
	v_pk_fma_f32 v[92:93], v[226:227], v[214:215], v[92:93] op_sel:[0,1,0]
	v_add_f32_dpp v232, v232, v232 row_half_mirror row_mask:0xf bank_mask:0xf
	v_pk_fma_f32 v[94:95], v[226:227], v[216:217], v[94:95] op_sel_hi:[1,0,1]
	v_add_f32_dpp v233, v233, v233 row_half_mirror row_mask:0xf bank_mask:0xf
	v_pk_fma_f32 v[96:97], v[226:227], v[216:217], v[96:97] op_sel:[0,1,0]
	ds_read_b128 v[54:57], v240 offset:17408
	ds_read_b128 v[58:61], v240 offset:17424
	ds_read_b128 v[62:65], v241 offset:1024
	ds_read_b128 v[66:69], v241 offset:1040
	ds_read_b64 v[78:79], v242 offset:1024
	s_waitcnt lgkmcnt(10)
	v_pk_fma_f32 v[234:235], v[230:231], v[228:229], v[232:233] op_sel_hi:[1,0,1] neg_lo:[1,0,0] neg_hi:[1,0,0]
	v_pk_fma_f32 v[170:171], v[230:231], v[218:219], v[82:83] op_sel_hi:[1,0,1] neg_lo:[1,0,0] neg_hi:[1,0,0]
	v_pk_fma_f32 v[172:173], v[230:231], v[218:219], v[84:85] op_sel:[0,1,0] neg_lo:[1,0,0] neg_hi:[1,0,0]
	v_pk_fma_f32 v[174:175], v[230:231], v[220:221], v[86:87] op_sel_hi:[1,0,1] neg_lo:[1,0,0] neg_hi:[1,0,0]
	v_pk_fma_f32 v[176:177], v[230:231], v[220:221], v[88:89] op_sel:[0,1,0] neg_lo:[1,0,0] neg_hi:[1,0,0]
	v_pk_fma_f32 v[178:179], v[230:231], v[222:223], v[90:91] op_sel_hi:[1,0,1] neg_lo:[1,0,0] neg_hi:[1,0,0]
	v_pk_fma_f32 v[180:181], v[230:231], v[222:223], v[92:93] op_sel:[0,1,0] neg_lo:[1,0,0] neg_hi:[1,0,0]
	v_pk_fma_f32 v[182:183], v[230:231], v[224:225], v[94:95] op_sel_hi:[1,0,1] neg_lo:[1,0,0] neg_hi:[1,0,0]
	v_pk_fma_f32 v[184:185], v[230:231], v[224:225], v[96:97] op_sel:[0,1,0] neg_lo:[1,0,0] neg_hi:[1,0,0]
	v_pk_fma_f32 v[234:235], v[226:227], v[228:229], v[234:235] op_sel:[0,1,0]
	ds_read_b128 v[70:73], v240 offset:50176
	ds_read_b128 v[74:77], v240 offset:50192
	ds_read_b64 v[80:81], v243 offset:32
	s_mov_b64 exec, s[60:61]
	ds_write_b64 v242, v[234:235] offset:17152
	s_mov_b64 exec, -1
	s_waitcnt lgkmcnt(9)
	v_pk_mul_f32 v[230:231], v[170:171], v[38:39] op_sel_hi:[1,0]
	v_pk_mul_f32 v[232:233], v[170:171], v[46:47] op_sel_hi:[1,0]
	v_pk_fma_f32 v[230:231], v[172:173], v[38:39], v[230:231] op_sel:[0,1,0]
	v_pk_fma_f32 v[232:233], v[172:173], v[46:47], v[232:233] op_sel:[0,1,0]
	v_pk_fma_f32 v[230:231], v[174:175], v[40:41], v[230:231] op_sel_hi:[1,0,1]
	v_pk_fma_f32 v[232:233], v[174:175], v[48:49], v[232:233] op_sel_hi:[1,0,1]
	v_pk_fma_f32 v[230:231], v[176:177], v[40:41], v[230:231] op_sel:[0,1,0]
	v_pk_fma_f32 v[232:233], v[176:177], v[48:49], v[232:233] op_sel:[0,1,0]
	v_pk_fma_f32 v[230:231], v[178:179], v[42:43], v[230:231] op_sel_hi:[1,0,1]
	v_pk_fma_f32 v[232:233], v[178:179], v[50:51], v[232:233] op_sel_hi:[1,0,1]
	v_pk_fma_f32 v[230:231], v[180:181], v[42:43], v[230:231] op_sel:[0,1,0]
	v_pk_fma_f32 v[232:233], v[180:181], v[50:51], v[232:233] op_sel:[0,1,0]
	v_pk_fma_f32 v[230:231], v[182:183], v[44:45], v[230:231] op_sel_hi:[1,0,1]
	v_pk_fma_f32 v[232:233], v[182:183], v[52:53], v[232:233] op_sel_hi:[1,0,1]
	v_pk_fma_f32 v[230:231], v[184:185], v[44:45], v[230:231] op_sel:[0,1,0]
	v_pk_fma_f32 v[232:233], v[184:185], v[52:53], v[232:233] op_sel:[0,1,0]
	ds_read_b128 v[186:189], v240 offset:34048
	ds_read_b128 v[190:193], v240 offset:34064
	ds_read_b128 v[194:197], v240 offset:1280
	ds_read_b128 v[198:201], v240 offset:1296
	s_waitcnt lgkmcnt(8)
; __device__ __forceinline__ void phase_rw_scan(KP P, const Ctx& c) {
;     ...
;             RW_LLOAD(A, 0);
; #pragma unroll 1
;             for (int tk = 0; tk < 64; tk += 2) {
;                 RW_LLOAD(B, tk + 1);
;                 RW_STEP(A, tk);
;                 RW_LLOAD(A, (tk + 2) & 63);
;                 RW_STEP(B, tk + 1);
;             }
	v_pk_mul_f32 v[82:83], v[170:171], v[54:55] op_sel_hi:[1,0]
	v_pk_mul_f32 v[84:85], v[172:173], v[54:55] op_sel:[0,1]
	v_pk_mul_f32 v[86:87], v[174:175], v[56:57] op_sel_hi:[1,0]
	v_pk_mul_f32 v[88:89], v[176:177], v[56:57] op_sel:[0,1]
	v_add_f32_dpp v230, v230, v230 quad_perm:[1,0,3,2] row_mask:0xf bank_mask:0xf
	v_pk_mul_f32 v[90:91], v[178:179], v[58:59] op_sel_hi:[1,0]
	v_add_f32_dpp v231, v231, v231 quad_perm:[1,0,3,2] row_mask:0xf bank_mask:0xf
	v_pk_mul_f32 v[92:93], v[180:181], v[58:59] op_sel:[0,1]
	v_add_f32_dpp v232, v232, v232 quad_perm:[1,0,3,2] row_mask:0xf bank_mask:0xf
	v_pk_mul_f32 v[94:95], v[182:183], v[60:61] op_sel_hi:[1,0]
	v_add_f32_dpp v233, v233, v233 quad_perm:[1,0,3,2] row_mask:0xf bank_mask:0xf
	v_pk_mul_f32 v[96:97], v[184:185], v[60:61] op_sel:[0,1]
	v_add_f32_dpp v230, v230, v230 quad_perm:[2,3,0,1] row_mask:0xf bank_mask:0xf
	v_pk_fma_f32 v[82:83], v[78:79], v[62:63], v[82:83] op_sel_hi:[1,0,1]
	v_add_f32_dpp v231, v231, v231 quad_perm:[2,3,0,1] row_mask:0xf bank_mask:0xf
	v_pk_fma_f32 v[84:85], v[78:79], v[62:63], v[84:85] op_sel:[0,1,0]
	v_add_f32_dpp v232, v232, v232 quad_perm:[2,3,0,1] row_mask:0xf bank_mask:0xf
	v_pk_fma_f32 v[86:87], v[78:79], v[64:65], v[86:87] op_sel_hi:[1,0,1]
	v_add_f32_dpp v233, v233, v233 quad_perm:[2,3,0,1] row_mask:0xf bank_mask:0xf
	v_pk_fma_f32 v[88:89], v[78:79], v[64:65], v[88:89] op_sel:[0,1,0]
	v_add_f32_dpp v230, v230, v230 row_half_mirror row_mask:0xf bank_mask:0xf
	v_pk_fma_f32 v[90:91], v[78:79], v[66:67], v[90:91] op_sel_hi:[1,0,1]
	v_add_f32_dpp v231, v231, v231 row_half_mirror row_mask:0xf bank_mask:0xf
	v_pk_fma_f32 v[92:93], v[78:79], v[66:67], v[92:93] op_sel:[0,1,0]
	v_add_f32_dpp v232, v232, v232 row_half_mirror row_mask:0xf bank_mask:0xf
	v_pk_fma_f32 v[94:95], v[78:79], v[68:69], v[94:95] op_sel_hi:[1,0,1]
	v_add_f32_dpp v233, v233, v233 row_half_mirror row_mask:0xf bank_mask:0xf
	v_pk_fma_f32 v[96:97], v[78:79], v[68:69], v[96:97] op_sel:[0,1,0]
	ds_read_b128 v[202:205], v240 offset:17664
	ds_read_b128 v[206:209], v240 offset:17680
	ds_read_b128 v[210:213], v241 offset:1280
	ds_read_b128 v[214:217], v241 offset:1296
	ds_read_b64 v[226:227], v242 offset:1280
	s_waitcnt lgkmcnt(10)
	v_pk_fma_f32 v[234:235], v[230:231], v[80:81], v[232:233] op_sel_hi:[1,0,1] neg_lo:[1,0,0] neg_hi:[1,0,0]
	v_pk_fma_f32 v[170:171], v[230:231], v[70:71], v[82:83] op_sel_hi:[1,0,1] neg_lo:[1,0,0] neg_hi:[1,0,0]
	v_pk_fma_f32 v[172:173], v[230:231], v[70:71], v[84:85] op_sel:[0,1,0] neg_lo:[1,0,0] neg_hi:[1,0,0]
	v_pk_fma_f32 v[174:175], v[230:231], v[72:73], v[86:87] op_sel_hi:[1,0,1] neg_lo:[1,0,0] neg_hi:[1,0,0]
	v_pk_fma_f32 v[176:177], v[230:231], v[72:73], v[88:89] op_sel:[0,1,0] neg_lo:[1,0,0] neg_hi:[1,0,0]
	v_pk_fma_f32 v[178:179], v[230:231], v[74:75], v[90:91] op_sel_hi:[1,0,1] neg_lo:[1,0,0] neg_hi:[1,0,0]
	v_pk_fma_f32 v[180:181], v[230:231], v[74:75], v[92:93] op_sel:[0,1,0] neg_lo:[1,0,0] neg_hi:[1,0,0]
	v_pk_fma_f32 v[182:183], v[230:231], v[76:77], v[94:95] op_sel_hi:[1,0,1] neg_lo:[1,0,0] neg_hi:[1,0,0]
	v_pk_fma_f32 v[184:185], v[230:231], v[76:77], v[96:97] op_sel:[0,1,0] neg_lo:[1,0,0] neg_hi:[1,0,0]
	v_pk_fma_f32 v[234:235], v[78:79], v[80:81], v[234:235] op_sel:[0,1,0]
	ds_read_b128 v[218:221], v240 offset:50432
	ds_read_b128 v[222:225], v240 offset:50448
	ds_read_b64 v[228:229], v243 offset:40
	s_mov_b64 exec, s[60:61]
	ds_write_b64 v242, v[234:235] offset:17408
	s_mov_b64 exec, -1
	s_waitcnt lgkmcnt(9)
	v_pk_mul_f32 v[230:231], v[170:171], v[186:187] op_sel_hi:[1,0]
	v_pk_mul_f32 v[232:233], v[170:171], v[194:195] op_sel_hi:[1,0]
	v_pk_fma_f32 v[230:231], v[172:173], v[186:187], v[230:231] op_sel:[0,1,0]
	v_pk_fma_f32 v[232:233], v[172:173], v[194:195], v[232:233] op_sel:[0,1,0]
	v_pk_fma_f32 v[230:231], v[174:175], v[188:189], v[230:231] op_sel_hi:[1,0,1]
	v_pk_fma_f32 v[232:233], v[174:175], v[196:197], v[232:233] op_sel_hi:[1,0,1]
	v_pk_fma_f32 v[230:231], v[176:177], v[188:189], v[230:231] op_sel:[0,1,0]
	v_pk_fma_f32 v[232:233], v[176:177], v[196:197], v[232:233] op_sel:[0,1,0]
	v_pk_fma_f32 v[230:231], v[178:179], v[190:191], v[230:231] op_sel_hi:[1,0,1]
	v_pk_fma_f32 v[232:233], v[178:179], v[198:199], v[232:233] op_sel_hi:[1,0,1]
	v_pk_fma_f32 v[230:231], v[180:181], v[190:191], v[230:231] op_sel:[0,1,0]
	v_pk_fma_f32 v[232:233], v[180:181], v[198:199], v[232:233] op_sel:[0,1,0]
	v_pk_fma_f32 v[230:231], v[182:183], v[192:193], v[230:231] op_sel_hi:[1,0,1]
	v_pk_fma_f32 v[232:233], v[182:183], v[200:201], v[232:233] op_sel_hi:[1,0,1]
	v_pk_fma_f32 v[230:231], v[184:185], v[192:193], v[230:231] op_sel:[0,1,0]
	v_pk_fma_f32 v[232:233], v[184:185], v[200:201], v[232:233] op_sel:[0,1,0]
	ds_read_b128 v[38:41], v240 offset:34304
	ds_read_b128 v[42:45], v240 offset:34320
	ds_read_b128 v[46:49], v240 offset:1536
	ds_read_b128 v[50:53], v240 offset:1552
	s_waitcnt lgkmcnt(8)
; __device__ __forceinline__ void phase_rw_scan(KP P, const Ctx& c) {
;     ...
;             RW_LLOAD(A, 0);
; #pragma unroll 1
;             for (int tk = 0; tk < 64; tk += 2) {
;                 RW_LLOAD(B, tk + 1);
;                 RW_STEP(A, tk);
;                 RW_LLOAD(A, (tk + 2) & 63);
;                 RW_STEP(B, tk + 1);
;             }
	v_pk_mul_f32 v[82:83], v[170:171], v[202:203] op_sel_hi:[1,0]
	v_pk_mul_f32 v[84:85], v[172:173], v[202:203] op_sel:[0,1]
	v_pk_mul_f32 v[86:87], v[174:175], v[204:205] op_sel_hi:[1,0]
	v_pk_mul_f32 v[88:89], v[176:177], v[204:205] op_sel:[0,1]
	v_add_f32_dpp v230, v230, v230 quad_perm:[1,0,3,2] row_mask:0xf bank_mask:0xf
	v_pk_mul_f32 v[90:91], v[178:179], v[206:207] op_sel_hi:[1,0]
	v_add_f32_dpp v231, v231, v231 quad_perm:[1,0,3,2] row_mask:0xf bank_mask:0xf
	v_pk_mul_f32 v[92:93], v[180:181], v[206:207] op_sel:[0,1]
	v_add_f32_dpp v232, v232, v232 quad_perm:[1,0,3,2] row_mask:0xf bank_mask:0xf
	v_pk_mul_f32 v[94:95], v[182:183], v[208:209] op_sel_hi:[1,0]
	v_add_f32_dpp v233, v233, v233 quad_perm:[1,0,3,2] row_mask:0xf bank_mask:0xf
	v_pk_mul_f32 v[96:97], v[184:185], v[208:209] op_sel:[0,1]
	v_add_f32_dpp v230, v230, v230 quad_perm:[2,3,0,1] row_mask:0xf bank_mask:0xf
	v_pk_fma_f32 v[82:83], v[226:227], v[210:211], v[82:83] op_sel_hi:[1,0,1]
	v_add_f32_dpp v231, v231, v231 quad_perm:[2,3,0,1] row_mask:0xf bank_mask:0xf
	v_pk_fma_f32 v[84:85], v[226:227], v[210:211], v[84:85] op_sel:[0,1,0]
	v_add_f32_dpp v232, v232, v232 quad_perm:[2,3,0,1] row_mask:0xf bank_mask:0xf
	v_pk_fma_f32 v[86:87], v[226:227], v[212:213], v[86:87] op_sel_hi:[1,0,1]
	v_add_f32_dpp v233, v233, v233 quad_perm:[2,3,0,1] row_mask:0xf bank_mask:0xf
	v_pk_fma_f32 v[88:89], v[226:227], v[212:213], v[88:89] op_sel:[0,1,0]
	v_add_f32_dpp v230, v230, v230 row_half_mirror row_mask:0xf bank_mask:0xf
	v_pk_fma_f32 v[90:91], v[226:227], v[214:215], v[90:91] op_sel_hi:[1,0,1]
	v_add_f32_dpp v231, v231, v231 row_half_mirror row_mask:0xf bank_mask:0xf
	v_pk_fma_f32 v[92:93], v[226:227], v[214:215], v[92:93] op_sel:[0,1,0]
	v_add_f32_dpp v232, v232, v232 row_half_mirror row_mask:0xf bank_mask:0xf
	v_pk_fma_f32 v[94:95], v[226:227], v[216:217], v[94:95] op_sel_hi:[1,0,1]
	v_add_f32_dpp v233, v233, v233 row_half_mirror row_mask:0xf bank_mask:0xf
	v_pk_fma_f32 v[96:97], v[226:227], v[216:217], v[96:97] op_sel:[0,1,0]
	ds_read_b128 v[54:57], v240 offset:17920
	ds_read_b128 v[58:61], v240 offset:17936
	ds_read_b128 v[62:65], v241 offset:1536
	ds_read_b128 v[66:69], v241 offset:1552
	ds_read_b64 v[78:79], v242 offset:1536
	s_waitcnt lgkmcnt(10)
	v_pk_fma_f32 v[234:235], v[230:231], v[228:229], v[232:233] op_sel_hi:[1,0,1] neg_lo:[1,0,0] neg_hi:[1,0,0]
	v_pk_fma_f32 v[170:171], v[230:231], v[218:219], v[82:83] op_sel_hi:[1,0,1] neg_lo:[1,0,0] neg_hi:[1,0,0]
	v_pk_fma_f32 v[172:173], v[230:231], v[218:219], v[84:85] op_sel:[0,1,0] neg_lo:[1,0,0] neg_hi:[1,0,0]
	v_pk_fma_f32 v[174:175], v[230:231], v[220:221], v[86:87] op_sel_hi:[1,0,1] neg_lo:[1,0,0] neg_hi:[1,0,0]
	v_pk_fma_f32 v[176:177], v[230:231], v[220:221], v[88:89] op_sel:[0,1,0] neg_lo:[1,0,0] neg_hi:[1,0,0]
	v_pk_fma_f32 v[178:179], v[230:231], v[222:223], v[90:91] op_sel_hi:[1,0,1] neg_lo:[1,0,0] neg_hi:[1,0,0]
	v_pk_fma_f32 v[180:181], v[230:231], v[222:223], v[92:93] op_sel:[0,1,0] neg_lo:[1,0,0] neg_hi:[1,0,0]
	v_pk_fma_f32 v[182:183], v[230:231], v[224:225], v[94:95] op_sel_hi:[1,0,1] neg_lo:[1,0,0] neg_hi:[1,0,0]
	v_pk_fma_f32 v[184:185], v[230:231], v[224:225], v[96:97] op_sel:[0,1,0] neg_lo:[1,0,0] neg_hi:[1,0,0]
	v_pk_fma_f32 v[234:235], v[226:227], v[228:229], v[234:235] op_sel:[0,1,0]
	ds_read_b128 v[70:73], v240 offset:50688
	ds_read_b128 v[74:77], v240 offset:50704
	ds_read_b64 v[80:81], v243 offset:48
	s_mov_b64 exec, s[60:61]
	ds_write_b64 v242, v[234:235] offset:17664
	s_mov_b64 exec, -1
	s_waitcnt lgkmcnt(9)
	v_pk_mul_f32 v[230:231], v[170:171], v[38:39] op_sel_hi:[1,0]
	v_pk_mul_f32 v[232:233], v[170:171], v[46:47] op_sel_hi:[1,0]
	v_pk_fma_f32 v[230:231], v[172:173], v[38:39], v[230:231] op_sel:[0,1,0]
	v_pk_fma_f32 v[232:233], v[172:173], v[46:47], v[232:233] op_sel:[0,1,0]
	v_pk_fma_f32 v[230:231], v[174:175], v[40:41], v[230:231] op_sel_hi:[1,0,1]
	v_pk_fma_f32 v[232:233], v[174:175], v[48:49], v[232:233] op_sel_hi:[1,0,1]
	v_pk_fma_f32 v[230:231], v[176:177], v[40:41], v[230:231] op_sel:[0,1,0]
	v_pk_fma_f32 v[232:233], v[176:177], v[48:49], v[232:233] op_sel:[0,1,0]
	v_pk_fma_f32 v[230:231], v[178:179], v[42:43], v[230:231] op_sel_hi:[1,0,1]
	v_pk_fma_f32 v[232:233], v[178:179], v[50:51], v[232:233] op_sel_hi:[1,0,1]
	v_pk_fma_f32 v[230:231], v[180:181], v[42:43], v[230:231] op_sel:[0,1,0]
	v_pk_fma_f32 v[232:233], v[180:181], v[50:51], v[232:233] op_sel:[0,1,0]
	v_pk_fma_f32 v[230:231], v[182:183], v[44:45], v[230:231] op_sel_hi:[1,0,1]
	v_pk_fma_f32 v[232:233], v[182:183], v[52:53], v[232:233] op_sel_hi:[1,0,1]
	v_pk_fma_f32 v[230:231], v[184:185], v[44:45], v[230:231] op_sel:[0,1,0]
	v_pk_fma_f32 v[232:233], v[184:185], v[52:53], v[232:233] op_sel:[0,1,0]
	ds_read_b128 v[186:189], v240 offset:34560
	ds_read_b128 v[190:193], v240 offset:34576
	ds_read_b128 v[194:197], v240 offset:1792
	ds_read_b128 v[198:201], v240 offset:1808
	s_waitcnt lgkmcnt(8)
; __device__ __forceinline__ void phase_rw_scan(KP P, const Ctx& c) {
;     ...
;             RW_LLOAD(A, 0);
; #pragma unroll 1
;             for (int tk = 0; tk < 64; tk += 2) {
;                 RW_LLOAD(B, tk + 1);
;                 RW_STEP(A, tk);
;                 RW_LLOAD(A, (tk + 2) & 63);
;                 RW_STEP(B, tk + 1);
;             }
	v_pk_mul_f32 v[82:83], v[170:171], v[54:55] op_sel_hi:[1,0]
	v_pk_mul_f32 v[84:85], v[172:173], v[54:55] op_sel:[0,1]
	v_pk_mul_f32 v[86:87], v[174:175], v[56:57] op_sel_hi:[1,0]
	v_pk_mul_f32 v[88:89], v[176:177], v[56:57] op_sel:[0,1]
	v_add_f32_dpp v230, v230, v230 quad_perm:[1,0,3,2] row_mask:0xf bank_mask:0xf
	v_pk_mul_f32 v[90:91], v[178:179], v[58:59] op_sel_hi:[1,0]
	v_add_f32_dpp v231, v231, v231 quad_perm:[1,0,3,2] row_mask:0xf bank_mask:0xf
	v_pk_mul_f32 v[92:93], v[180:181], v[58:59] op_sel:[0,1]
	v_add_f32_dpp v232, v232, v232 quad_perm:[1,0,3,2] row_mask:0xf bank_mask:0xf
	v_pk_mul_f32 v[94:95], v[182:183], v[60:61] op_sel_hi:[1,0]
	v_add_f32_dpp v233, v233, v233 quad_perm:[1,0,3,2] row_mask:0xf bank_mask:0xf
	v_pk_mul_f32 v[96:97], v[184:185], v[60:61] op_sel:[0,1]
	v_add_f32_dpp v230, v230, v230 quad_perm:[2,3,0,1] row_mask:0xf bank_mask:0xf
	v_pk_fma_f32 v[82:83], v[78:79], v[62:63], v[82:83] op_sel_hi:[1,0,1]
	v_add_f32_dpp v231, v231, v231 quad_perm:[2,3,0,1] row_mask:0xf bank_mask:0xf
	v_pk_fma_f32 v[84:85], v[78:79], v[62:63], v[84:85] op_sel:[0,1,0]
	v_add_f32_dpp v232, v232, v232 quad_perm:[2,3,0,1] row_mask:0xf bank_mask:0xf
	v_pk_fma_f32 v[86:87], v[78:79], v[64:65], v[86:87] op_sel_hi:[1,0,1]
	v_add_f32_dpp v233, v233, v233 quad_perm:[2,3,0,1] row_mask:0xf bank_mask:0xf
	v_pk_fma_f32 v[88:89], v[78:79], v[64:65], v[88:89] op_sel:[0,1,0]
	v_add_f32_dpp v230, v230, v230 row_half_mirror row_mask:0xf bank_mask:0xf
	v_pk_fma_f32 v[90:91], v[78:79], v[66:67], v[90:91] op_sel_hi:[1,0,1]
	v_add_f32_dpp v231, v231, v231 row_half_mirror row_mask:0xf bank_mask:0xf
	v_pk_fma_f32 v[92:93], v[78:79], v[66:67], v[92:93] op_sel:[0,1,0]
	v_add_f32_dpp v232, v232, v232 row_half_mirror row_mask:0xf bank_mask:0xf
	v_pk_fma_f32 v[94:95], v[78:79], v[68:69], v[94:95] op_sel_hi:[1,0,1]
	v_add_f32_dpp v233, v233, v233 row_half_mirror row_mask:0xf bank_mask:0xf
	v_pk_fma_f32 v[96:97], v[78:79], v[68:69], v[96:97] op_sel:[0,1,0]
	ds_read_b128 v[202:205], v240 offset:18176
	ds_read_b128 v[206:209], v240 offset:18192
	ds_read_b128 v[210:213], v241 offset:1792
	ds_read_b128 v[214:217], v241 offset:1808
	ds_read_b64 v[226:227], v242 offset:1792
	s_waitcnt lgkmcnt(10)
	v_pk_fma_f32 v[234:235], v[230:231], v[80:81], v[232:233] op_sel_hi:[1,0,1] neg_lo:[1,0,0] neg_hi:[1,0,0]
	v_pk_fma_f32 v[170:171], v[230:231], v[70:71], v[82:83] op_sel_hi:[1,0,1] neg_lo:[1,0,0] neg_hi:[1,0,0]
	v_pk_fma_f32 v[172:173], v[230:231], v[70:71], v[84:85] op_sel:[0,1,0] neg_lo:[1,0,0] neg_hi:[1,0,0]
	v_pk_fma_f32 v[174:175], v[230:231], v[72:73], v[86:87] op_sel_hi:[1,0,1] neg_lo:[1,0,0] neg_hi:[1,0,0]
	v_pk_fma_f32 v[176:177], v[230:231], v[72:73], v[88:89] op_sel:[0,1,0] neg_lo:[1,0,0] neg_hi:[1,0,0]
	v_pk_fma_f32 v[178:179], v[230:231], v[74:75], v[90:91] op_sel_hi:[1,0,1] neg_lo:[1,0,0] neg_hi:[1,0,0]
	v_pk_fma_f32 v[180:181], v[230:231], v[74:75], v[92:93] op_sel:[0,1,0] neg_lo:[1,0,0] neg_hi:[1,0,0]
	v_pk_fma_f32 v[182:183], v[230:231], v[76:77], v[94:95] op_sel_hi:[1,0,1] neg_lo:[1,0,0] neg_hi:[1,0,0]
	v_pk_fma_f32 v[184:185], v[230:231], v[76:77], v[96:97] op_sel:[0,1,0] neg_lo:[1,0,0] neg_hi:[1,0,0]
	v_pk_fma_f32 v[234:235], v[78:79], v[80:81], v[234:235] op_sel:[0,1,0]
	ds_read_b128 v[218:221], v240 offset:50944
	ds_read_b128 v[222:225], v240 offset:50960
	ds_read_b64 v[228:229], v243 offset:56
	s_mov_b64 exec, s[60:61]
	ds_write_b64 v242, v[234:235] offset:17920
	s_mov_b64 exec, -1
	s_waitcnt lgkmcnt(9)
	v_pk_mul_f32 v[230:231], v[170:171], v[186:187] op_sel_hi:[1,0]
	v_pk_mul_f32 v[232:233], v[170:171], v[194:195] op_sel_hi:[1,0]
	v_pk_fma_f32 v[230:231], v[172:173], v[186:187], v[230:231] op_sel:[0,1,0]
	v_pk_fma_f32 v[232:233], v[172:173], v[194:195], v[232:233] op_sel:[0,1,0]
	v_pk_fma_f32 v[230:231], v[174:175], v[188:189], v[230:231] op_sel_hi:[1,0,1]
	v_pk_fma_f32 v[232:233], v[174:175], v[196:197], v[232:233] op_sel_hi:[1,0,1]
	v_pk_fma_f32 v[230:231], v[176:177], v[188:189], v[230:231] op_sel:[0,1,0]
	v_pk_fma_f32 v[232:233], v[176:177], v[196:197], v[232:233] op_sel:[0,1,0]
	v_pk_fma_f32 v[230:231], v[178:179], v[190:191], v[230:231] op_sel_hi:[1,0,1]
	v_pk_fma_f32 v[232:233], v[178:179], v[198:199], v[232:233] op_sel_hi:[1,0,1]
	v_pk_fma_f32 v[230:231], v[180:181], v[190:191], v[230:231] op_sel:[0,1,0]
	v_pk_fma_f32 v[232:233], v[180:181], v[198:199], v[232:233] op_sel:[0,1,0]
	v_pk_fma_f32 v[230:231], v[182:183], v[192:193], v[230:231] op_sel_hi:[1,0,1]
	v_pk_fma_f32 v[232:233], v[182:183], v[200:201], v[232:233] op_sel_hi:[1,0,1]
	v_pk_fma_f32 v[230:231], v[184:185], v[192:193], v[230:231] op_sel:[0,1,0]
	v_pk_fma_f32 v[232:233], v[184:185], v[200:201], v[232:233] op_sel:[0,1,0]
	ds_read_b128 v[38:41], v240 offset:34816
	ds_read_b128 v[42:45], v240 offset:34832
	ds_read_b128 v[46:49], v240 offset:2048
	ds_read_b128 v[50:53], v240 offset:2064
	s_waitcnt lgkmcnt(8)
; __device__ __forceinline__ void phase_rw_scan(KP P, const Ctx& c) {
;     ...
;             RW_LLOAD(A, 0);
; #pragma unroll 1
;             for (int tk = 0; tk < 64; tk += 2) {
;                 RW_LLOAD(B, tk + 1);
;                 RW_STEP(A, tk);
;                 RW_LLOAD(A, (tk + 2) & 63);
;                 RW_STEP(B, tk + 1);
;             }
	v_pk_mul_f32 v[82:83], v[170:171], v[202:203] op_sel_hi:[1,0]
	v_pk_mul_f32 v[84:85], v[172:173], v[202:203] op_sel:[0,1]
	v_pk_mul_f32 v[86:87], v[174:175], v[204:205] op_sel_hi:[1,0]
	v_pk_mul_f32 v[88:89], v[176:177], v[204:205] op_sel:[0,1]
	v_add_f32_dpp v230, v230, v230 quad_perm:[1,0,3,2] row_mask:0xf bank_mask:0xf
	v_pk_mul_f32 v[90:91], v[178:179], v[206:207] op_sel_hi:[1,0]
	v_add_f32_dpp v231, v231, v231 quad_perm:[1,0,3,2] row_mask:0xf bank_mask:0xf
	v_pk_mul_f32 v[92:93], v[180:181], v[206:207] op_sel:[0,1]
	v_add_f32_dpp v232, v232, v232 quad_perm:[1,0,3,2] row_mask:0xf bank_mask:0xf
	v_pk_mul_f32 v[94:95], v[182:183], v[208:209] op_sel_hi:[1,0]
	v_add_f32_dpp v233, v233, v233 quad_perm:[1,0,3,2] row_mask:0xf bank_mask:0xf
	v_pk_mul_f32 v[96:97], v[184:185], v[208:209] op_sel:[0,1]
	v_add_f32_dpp v230, v230, v230 quad_perm:[2,3,0,1] row_mask:0xf bank_mask:0xf
	v_pk_fma_f32 v[82:83], v[226:227], v[210:211], v[82:83] op_sel_hi:[1,0,1]
	v_add_f32_dpp v231, v231, v231 quad_perm:[2,3,0,1] row_mask:0xf bank_mask:0xf
	v_pk_fma_f32 v[84:85], v[226:227], v[210:211], v[84:85] op_sel:[0,1,0]
	v_add_f32_dpp v232, v232, v232 quad_perm:[2,3,0,1] row_mask:0xf bank_mask:0xf
	v_pk_fma_f32 v[86:87], v[226:227], v[212:213], v[86:87] op_sel_hi:[1,0,1]
	v_add_f32_dpp v233, v233, v233 quad_perm:[2,3,0,1] row_mask:0xf bank_mask:0xf
	v_pk_fma_f32 v[88:89], v[226:227], v[212:213], v[88:89] op_sel:[0,1,0]
	v_add_f32_dpp v230, v230, v230 row_half_mirror row_mask:0xf bank_mask:0xf
	v_pk_fma_f32 v[90:91], v[226:227], v[214:215], v[90:91] op_sel_hi:[1,0,1]
	v_add_f32_dpp v231, v231, v231 row_half_mirror row_mask:0xf bank_mask:0xf
	v_pk_fma_f32 v[92:93], v[226:227], v[214:215], v[92:93] op_sel:[0,1,0]
	v_add_f32_dpp v232, v232, v232 row_half_mirror row_mask:0xf bank_mask:0xf
	v_pk_fma_f32 v[94:95], v[226:227], v[216:217], v[94:95] op_sel_hi:[1,0,1]
	v_add_f32_dpp v233, v233, v233 row_half_mirror row_mask:0xf bank_mask:0xf
	v_pk_fma_f32 v[96:97], v[226:227], v[216:217], v[96:97] op_sel:[0,1,0]
	ds_read_b128 v[54:57], v240 offset:18432
	ds_read_b128 v[58:61], v240 offset:18448
	ds_read_b128 v[62:65], v241 offset:2048
	ds_read_b128 v[66:69], v241 offset:2064
	ds_read_b64 v[78:79], v242 offset:2048
	s_waitcnt lgkmcnt(10)
	v_pk_fma_f32 v[234:235], v[230:231], v[228:229], v[232:233] op_sel_hi:[1,0,1] neg_lo:[1,0,0] neg_hi:[1,0,0]
	v_pk_fma_f32 v[170:171], v[230:231], v[218:219], v[82:83] op_sel_hi:[1,0,1] neg_lo:[1,0,0] neg_hi:[1,0,0]
	v_pk_fma_f32 v[172:173], v[230:231], v[218:219], v[84:85] op_sel:[0,1,0] neg_lo:[1,0,0] neg_hi:[1,0,0]
	v_pk_fma_f32 v[174:175], v[230:231], v[220:221], v[86:87] op_sel_hi:[1,0,1] neg_lo:[1,0,0] neg_hi:[1,0,0]
	v_pk_fma_f32 v[176:177], v[230:231], v[220:221], v[88:89] op_sel:[0,1,0] neg_lo:[1,0,0] neg_hi:[1,0,0]
	v_pk_fma_f32 v[178:179], v[230:231], v[222:223], v[90:91] op_sel_hi:[1,0,1] neg_lo:[1,0,0] neg_hi:[1,0,0]
	v_pk_fma_f32 v[180:181], v[230:231], v[222:223], v[92:93] op_sel:[0,1,0] neg_lo:[1,0,0] neg_hi:[1,0,0]
	v_pk_fma_f32 v[182:183], v[230:231], v[224:225], v[94:95] op_sel_hi:[1,0,1] neg_lo:[1,0,0] neg_hi:[1,0,0]
	v_pk_fma_f32 v[184:185], v[230:231], v[224:225], v[96:97] op_sel:[0,1,0] neg_lo:[1,0,0] neg_hi:[1,0,0]
	v_pk_fma_f32 v[234:235], v[226:227], v[228:229], v[234:235] op_sel:[0,1,0]
	ds_read_b128 v[70:73], v240 offset:51200
	ds_read_b128 v[74:77], v240 offset:51216
	ds_read_b64 v[80:81], v243 offset:64
	s_mov_b64 exec, s[60:61]
	ds_write_b64 v242, v[234:235] offset:18176
	s_mov_b64 exec, -1
	v_add_u32_e32 v240, 0x800, v240
	v_add_u32_e32 v241, 0x800, v241
	v_add_u32_e32 v242, 0x800, v242
	v_add_u32_e32 v243, 0x40, v243
	s_add_i32 s62, s62, 1
	s_cmp_lt_u32 s62, 8
	s_cbranch_scc1 .Lrw_loop
	s_branch .LBB0_1754
